# v18 plus lnstats fast path: all 8 row loads per wave issued up front with counted vmcnt waits
# baseline (speedup 1.0000x reference)
; DI float bflo(unsigned w) { return __uint_as_float(w << 16); }
; DI float bfhi(unsigned w) { return __uint_as_float(w & 0xffff0000u); }
; DI void phase_lnstats(const bf16_t* GV, f32x2* STATS, int G) {
;     ...
;     for (int m = gw; m < MH; m += NGW) {
;         const bf16_t* p = GV + (size_t)m * D + 16 * lane;
;         const u32x4 a0 = *(const u32x4*)p, a1 = *(const u32x4*)(p + 8);
;         const unsigned aw[8] = {a0.x, a0.y, a0.z, a0.w, a1.x, a1.y, a1.z, a1.w};
;         float s1 = 0.f, s2 = 0.f;
; #pragma unroll
;         for (int w = 0; w < 8; ++w) { const float x0 = bflo(aw[w]), x1 = bfhi(aw[w]); s1 += x0 + x1; s2 += x0 * x0 + x1 * x1; }
;         s1 = wave_sum(s1); s2 = wave_sum(s2);
;         const float mean = s1 * (1.0f / D), var = fmaxf(s2 * (1.0f / D) - mean * mean, 0.f);
;         if (lane == 0) STATS[m] = (f32x2){mean, rsqrtf(var + 1e-5f)};
.LBB0_157:
	s_and_b64 vcc, exec, s[0:1]
	s_cbranch_vccz .LBB0_206
	s_cmp_gt_i32 s28, 0
	s_mov_b64 s[0:1], -1
	s_cbranch_scc0 .LBB0_204
	v_mov_b32_e32 v0, v136
	v_readlane_b32 s1, v243, 40
	v_readfirstlane_b32 s0, v0
	s_ashr_i32 s0, s0, 6
	s_add_i32 s2, s0, s1
	v_readlane_b32 s10, v242, 55
	s_cmpk_gt_i32 s2, 0x3fff
	v_readlane_b32 s11, v242, 56
	s_cbranch_scc1 .LBB0_164
	v_and_b32_e32 v1, 64, v176
	v_add_u32_e32 v1, 64, v1
	v_xor_b32_e32 v2, 1, v176
	v_cmp_lt_i32_e32 vcc, v2, v1
	s_ashr_i32 s3, s2, 31
	s_lshl_b64 s[0:1], s[2:3], 3
	v_cndmask_b32_e32 v2, v176, v2, vcc
	v_lshlrev_b32_e32 v6, 2, v2
	v_xor_b32_e32 v2, 2, v176
	v_cmp_lt_i32_e32 vcc, v2, v1
	s_add_u32 s6, s96, s0
	s_addc_u32 s7, s97, s1
	v_cndmask_b32_e32 v2, v176, v2, vcc
	v_lshlrev_b32_e32 v7, 2, v2
	v_xor_b32_e32 v2, 4, v176
	v_cmp_lt_i32_e32 vcc, v2, v1
	s_lshl_b64 s[0:1], s[2:3], 11
	v_and_b32_e32 v0, 63, v0
	v_cndmask_b32_e32 v2, v176, v2, vcc
	v_lshlrev_b32_e32 v8, 2, v2
	v_xor_b32_e32 v2, 8, v176
	v_cmp_lt_i32_e32 vcc, v2, v1
	s_add_u32 s0, s76, s0
	v_lshlrev_b32_e32 v48, 5, v0
	v_cndmask_b32_e32 v2, v176, v2, vcc
	v_lshlrev_b32_e32 v9, 2, v2
	v_xor_b32_e32 v2, 16, v176
	v_cmp_lt_i32_e32 vcc, v2, v1
	s_addc_u32 s1, s77, s1
	s_nop 0
	v_cndmask_b32_e32 v2, v176, v2, vcc
	v_lshlrev_b32_e32 v10, 2, v2
	v_xor_b32_e32 v2, 32, v176
	v_cmp_lt_i32_e32 vcc, v2, v1
	s_nop 1
	v_cndmask_b32_e32 v1, v176, v2, vcc
	v_lshlrev_b32_e32 v11, 2, v1
	v_cmp_eq_u32_e32 vcc, 0, v0
	v_lshl_add_u64 v[0:1], s[0:1], 0, v[48:49]
	s_cmpk_lg_i32 s4, 0x800
	s_cbranch_scc1 .LBB0_162
	global_load_dwordx4 v[28:31], v48, s[0:1] offset:16
	global_load_dwordx4 v[32:35], v48, s[0:1]
	s_add_u32 s0, s0, s34
	s_addc_u32 s1, s1, s35
	global_load_dwordx4 v[36:39], v48, s[0:1] offset:16
	global_load_dwordx4 v[40:43], v48, s[0:1]
	s_add_u32 s0, s0, s34
	s_addc_u32 s1, s1, s35
	global_load_dwordx4 v[50:53], v48, s[0:1] offset:16
	global_load_dwordx4 v[54:57], v48, s[0:1]
	s_add_u32 s0, s0, s34
	s_addc_u32 s1, s1, s35
	global_load_dwordx4 v[58:61], v48, s[0:1] offset:16
	global_load_dwordx4 v[62:65], v48, s[0:1]
	s_add_u32 s0, s0, s34
	s_addc_u32 s1, s1, s35
	global_load_dwordx4 v[66:69], v48, s[0:1] offset:16
	global_load_dwordx4 v[70:73], v48, s[0:1]
	s_add_u32 s0, s0, s34
	s_addc_u32 s1, s1, s35
	global_load_dwordx4 v[74:77], v48, s[0:1] offset:16
	global_load_dwordx4 v[78:81], v48, s[0:1]
	s_add_u32 s0, s0, s34
	s_addc_u32 s1, s1, s35
	global_load_dwordx4 v[82:85], v48, s[0:1] offset:16
	global_load_dwordx4 v[86:89], v48, s[0:1]
	s_add_u32 s0, s0, s34
	s_addc_u32 s1, s1, s35
	global_load_dwordx4 v[90:93], v48, s[0:1] offset:16
	global_load_dwordx4 v[94:97], v48, s[0:1]
	s_mov_b32 s3, 0
.Lln_fast_loop:
	s_cmp_eq_u32 s3, 0
	s_cbranch_scc1 .Lln_fast_c0
	s_cmp_eq_u32 s3, 1
	s_cbranch_scc1 .Lln_fast_c1
	s_cmp_eq_u32 s3, 2
	s_cbranch_scc1 .Lln_fast_c2
	s_cmp_eq_u32 s3, 3
	s_cbranch_scc1 .Lln_fast_c3
	s_cmp_eq_u32 s3, 4
	s_cbranch_scc1 .Lln_fast_c4
	s_cmp_eq_u32 s3, 5
	s_cbranch_scc1 .Lln_fast_c5
	s_cmp_eq_u32 s3, 6
	s_cbranch_scc1 .Lln_fast_c6
	s_cmp_eq_u32 s3, 7
	s_cbranch_scc1 .Lln_fast_c7
	s_branch .LBB0_164
.Lln_fast_c0:
	s_waitcnt vmcnt(14) lgkmcnt(0)
	v_mov_b32_e32 v2, v28
	v_mov_b32_e32 v3, v29
	v_mov_b32_e32 v4, v30
	v_mov_b32_e32 v5, v31
	v_mov_b32_e32 v12, v32
	v_mov_b32_e32 v13, v33
	v_mov_b32_e32 v14, v34
	v_mov_b32_e32 v15, v35
	s_branch .Lln_fast_body
.Lln_fast_c1:
	s_waitcnt vmcnt(13) lgkmcnt(0)
	v_mov_b32_e32 v2, v36
	v_mov_b32_e32 v3, v37
	v_mov_b32_e32 v4, v38
	v_mov_b32_e32 v5, v39
	v_mov_b32_e32 v12, v40
	v_mov_b32_e32 v13, v41
	v_mov_b32_e32 v14, v42
	v_mov_b32_e32 v15, v43
	s_branch .Lln_fast_body
.Lln_fast_c2:
	s_waitcnt vmcnt(12) lgkmcnt(0)
	v_mov_b32_e32 v2, v50
	v_mov_b32_e32 v3, v51
	v_mov_b32_e32 v4, v52
	v_mov_b32_e32 v5, v53
	v_mov_b32_e32 v12, v54
	v_mov_b32_e32 v13, v55
	v_mov_b32_e32 v14, v56
	v_mov_b32_e32 v15, v57
	s_branch .Lln_fast_body
.Lln_fast_c3:
	s_waitcnt vmcnt(11) lgkmcnt(0)
	v_mov_b32_e32 v2, v58
	v_mov_b32_e32 v3, v59
	v_mov_b32_e32 v4, v60
	v_mov_b32_e32 v5, v61
	v_mov_b32_e32 v12, v62
	v_mov_b32_e32 v13, v63
	v_mov_b32_e32 v14, v64
	v_mov_b32_e32 v15, v65
	s_branch .Lln_fast_body
; DI float bflo(unsigned w) { return __uint_as_float(w << 16); }
; DI float bfhi(unsigned w) { return __uint_as_float(w & 0xffff0000u); }
; DI void phase_lnstats(const bf16_t* GV, f32x2* STATS, int G) {
;     ...
;     for (int m = gw; m < MH; m += NGW) {
;         const bf16_t* p = GV + (size_t)m * D + 16 * lane;
;         const u32x4 a0 = *(const u32x4*)p, a1 = *(const u32x4*)(p + 8);
;         const unsigned aw[8] = {a0.x, a0.y, a0.z, a0.w, a1.x, a1.y, a1.z, a1.w};
;         float s1 = 0.f, s2 = 0.f;
; #pragma unroll
;         for (int w = 0; w < 8; ++w) { const float x0 = bflo(aw[w]), x1 = bfhi(aw[w]); s1 += x0 + x1; s2 += x0 * x0 + x1 * x1; }
;         s1 = wave_sum(s1); s2 = wave_sum(s2);
;         const float mean = s1 * (1.0f / D), var = fmaxf(s2 * (1.0f / D) - mean * mean, 0.f);
;         if (lane == 0) STATS[m] = (f32x2){mean, rsqrtf(var + 1e-5f)};
.Lln_fast_c4:
	s_waitcnt vmcnt(10) lgkmcnt(0)
	v_mov_b32_e32 v2, v66
	v_mov_b32_e32 v3, v67
	v_mov_b32_e32 v4, v68
	v_mov_b32_e32 v5, v69
	v_mov_b32_e32 v12, v70
	v_mov_b32_e32 v13, v71
	v_mov_b32_e32 v14, v72
	v_mov_b32_e32 v15, v73
	s_branch .Lln_fast_body
.Lln_fast_c5:
	s_waitcnt vmcnt(9) lgkmcnt(0)
	v_mov_b32_e32 v2, v74
	v_mov_b32_e32 v3, v75
	v_mov_b32_e32 v4, v76
	v_mov_b32_e32 v5, v77
	v_mov_b32_e32 v12, v78
	v_mov_b32_e32 v13, v79
	v_mov_b32_e32 v14, v80
	v_mov_b32_e32 v15, v81
	s_branch .Lln_fast_body
.Lln_fast_c6:
	s_waitcnt vmcnt(8) lgkmcnt(0)
	v_mov_b32_e32 v2, v82
	v_mov_b32_e32 v3, v83
	v_mov_b32_e32 v4, v84
	v_mov_b32_e32 v5, v85
	v_mov_b32_e32 v12, v86
	v_mov_b32_e32 v13, v87
	v_mov_b32_e32 v14, v88
	v_mov_b32_e32 v15, v89
	s_branch .Lln_fast_body
.Lln_fast_c7:
	s_waitcnt vmcnt(7) lgkmcnt(0)
	v_mov_b32_e32 v2, v90
	v_mov_b32_e32 v3, v91
	v_mov_b32_e32 v4, v92
	v_mov_b32_e32 v5, v93
	v_mov_b32_e32 v12, v94
	v_mov_b32_e32 v13, v95
	v_mov_b32_e32 v14, v96
	v_mov_b32_e32 v15, v97
	s_branch .Lln_fast_body
.Lln_fast_body:
	v_lshlrev_b32_e32 v27, 16, v5
	v_and_b32_e32 v17, 0xffff0000, v12
	v_and_b32_e32 v19, 0xffff0000, v13
	v_lshlrev_b32_e32 v13, 16, v13
	v_lshlrev_b32_e32 v12, 16, v12
	v_lshlrev_b32_e32 v21, 16, v14
	v_and_b32_e32 v23, 0xffff0000, v14
	v_mul_f32_e32 v24, v12, v12
	v_mov_b32_e32 v14, v13
	v_mov_b32_e32 v25, v13
	v_mul_f32_e32 v18, v17, v17
	v_mul_f32_e32 v48, v19, v19
	v_pk_add_f32 v[18:19], v[24:25], v[18:19]
	v_pk_mul_f32 v[24:25], v[12:13], v[14:15] op_sel:[1,0] op_sel_hi:[0,1]
	v_pk_add_f32 v[12:13], v[12:13], v[16:17] op_sel:[1,0] op_sel_hi:[0,1]
	v_mov_b32_e32 v25, v13
	v_mul_f32_e32 v20, v21, v21
	v_mul_f32_e32 v22, v23, v23
	v_pk_add_f32 v[12:13], v[24:25], v[48:49]
	v_pk_add_f32 v[16:17], v[20:21], v[22:23]
	v_pk_add_f32 v[12:13], v[18:19], v[12:13]
	v_and_b32_e32 v19, 0xffff0000, v2
	v_pk_add_f32 v[12:13], v[16:17], v[12:13]
	v_lshlrev_b32_e32 v17, 16, v15
	v_and_b32_e32 v15, 0xffff0000, v15
	v_mul_f32_e32 v16, v17, v17
	v_mul_f32_e32 v14, v15, v15
	v_pk_add_f32 v[14:15], v[16:17], v[14:15]
	v_lshlrev_b32_e32 v17, 16, v2
	v_mul_f32_e32 v16, v17, v17
	v_mul_f32_e32 v18, v19, v19
	v_lshlrev_b32_e32 v21, 16, v3
	v_and_b32_e32 v3, 0xffff0000, v3
	v_mul_f32_e32 v20, v21, v21
	v_mul_f32_e32 v2, v3, v3
	v_lshlrev_b32_e32 v23, 16, v4
	v_and_b32_e32 v25, 0xffff0000, v4
	v_pk_add_f32 v[12:13], v[14:15], v[12:13]
	v_pk_add_f32 v[14:15], v[16:17], v[18:19]
	v_mul_f32_e32 v22, v23, v23
	v_mul_f32_e32 v24, v25, v25
	v_and_b32_e32 v5, 0xffff0000, v5
	v_pk_add_f32 v[12:13], v[14:15], v[12:13]
	v_pk_add_f32 v[2:3], v[20:21], v[2:3]
	v_mul_f32_e32 v26, v27, v27
	v_mul_f32_e32 v4, v5, v5
	v_pk_add_f32 v[2:3], v[2:3], v[12:13]
	v_pk_add_f32 v[12:13], v[22:23], v[24:25]
	v_pk_add_f32 v[4:5], v[26:27], v[4:5]
	v_pk_add_f32 v[2:3], v[12:13], v[2:3]
	s_nop 0
	v_pk_add_f32 v[2:3], v[4:5], v[2:3]
	ds_bpermute_b32 v5, v6, v3
	ds_bpermute_b32 v4, v6, v2
	s_waitcnt lgkmcnt(0)
	v_pk_add_f32 v[2:3], v[2:3], v[4:5]
	ds_bpermute_b32 v5, v7, v3
	ds_bpermute_b32 v4, v7, v2
	s_waitcnt lgkmcnt(0)
	v_pk_add_f32 v[2:3], v[2:3], v[4:5]
	ds_bpermute_b32 v5, v8, v3
	ds_bpermute_b32 v4, v8, v2
	s_waitcnt lgkmcnt(0)
	v_pk_add_f32 v[2:3], v[2:3], v[4:5]
	ds_bpermute_b32 v5, v9, v3
	ds_bpermute_b32 v4, v9, v2
	s_waitcnt lgkmcnt(0)
	v_pk_add_f32 v[2:3], v[2:3], v[4:5]
	ds_bpermute_b32 v5, v10, v3
	ds_bpermute_b32 v4, v10, v2
	s_waitcnt lgkmcnt(0)
	v_pk_add_f32 v[2:3], v[2:3], v[4:5]
	ds_bpermute_b32 v5, v11, v3
	ds_bpermute_b32 v4, v11, v2
	s_and_saveexec_b64 s[8:9], vcc
	s_cbranch_execz .Lln_fast_next
	s_waitcnt lgkmcnt(0)
	v_pk_add_f32 v[2:3], v[2:3], v[4:5]
	s_mov_b32 s0, 0x3a800000
	v_pk_mul_f32 v[2:3], v[2:3], s[0:1] op_sel_hi:[1,0]
	s_mov_b32 s0, 0x800000
	v_fma_f32 v2, -v3, v3, v2
	v_max_f32_e32 v2, 0, v2
	v_add_f32_e32 v2, 0x3727c5ac, v2
	v_mul_f32_e32 v4, 0x4b800000, v2
	v_cmp_gt_f32_e64 s[0:1], s0, v2
	s_nop 1
	v_cndmask_b32_e64 v2, v2, v4, s[0:1]
	v_rsq_f32_e32 v2, v2
	s_nop 0
	v_mul_f32_e32 v4, 0x45800000, v2
	v_cndmask_b32_e64 v5, v2, v4, s[0:1]
	v_mov_b32_e32 v4, v3
	global_store_dwordx2 v49, v[4:5], s[6:7]
	s_branch .Lln_fast_next
.Lln_fast_next:
	s_or_b64 exec, exec, s[8:9]
	s_add_i32 s3, s3, 1
	s_add_u32 s6, s6, s10
	s_addc_u32 s7, s7, s11
	s_cmp_lt_u32 s3, 8
	s_cbranch_scc1 .Lln_fast_loop
	s_branch .LBB0_164
